# cross-row softmax max/sum shuffles via v_permlane16/32_swap instead of ds_bpermute in MoBA and attnA items; census loads batched; MoBA prologue KM loads no longer waited one by one
# baseline (speedup 1.0000x reference)
; __device__ __forceinline__ unsigned xb_ld(unsigned* p)              { return __hip_atomic_load(p, __ATOMIC_RELAXED, __HIP_MEMORY_SCOPE_AGENT); }
; __device__ __forceinline__ void xcd_barrier_complete(unsigned* bar, unsigned x, unsigned& nloc, unsigned& nx) {
;     const unsigned G = gridDim.x * gridDim.y * gridDim.z;
;     unsigned sum, cnt, mine, sp = 0u;
;     for (;;) {
;         sum = 0u; cnt = 0u; mine = 0u;
; #pragma unroll
;         for (unsigned j = 0; j < 16; ++j) { const unsigned c = xb_ld(&bar[XB_XCNT(j)]); sum += c; cnt += (c > 0u) ? 1u : 0u; mine = (j == x) ? c : mine; }
;         if (sum == G) break;
;         __builtin_amdgcn_s_sleep(1);
;         if ((++sp & 255u) == 0u) { if (xb_ld(&bar[XB_TMO])) break; if (sp > XB_SPIN_CAP) { atomicAdd(&bar[XB_TMO], 1u); break; } }
;     }
;     nloc = mine > 0u ? mine : 1u; nx = cnt > 0u ? cnt : 1u;
; }
.LBB0_95:
	s_waitcnt lgkmcnt(0)
	global_load_dword v0, v193, s[58:59] sc1
	global_load_dword v1, v193, s[58:59] offset:256 sc1
	global_load_dword v2, v193, s[58:59] offset:512 sc1
	global_load_dword v3, v193, s[58:59] offset:768 sc1
	global_load_dword v4, v193, s[58:59] offset:1024 sc1
	global_load_dword v5, v193, s[58:59] offset:1280 sc1
	global_load_dword v6, v193, s[58:59] offset:1536 sc1
	global_load_dword v7, v193, s[58:59] offset:1792 sc1
	global_load_dword v8, v193, s[58:59] offset:2048 sc1
	global_load_dword v9, v193, s[58:59] offset:2304 sc1
	global_load_dword v10, v193, s[58:59] offset:2560 sc1
	global_load_dword v11, v193, s[58:59] offset:2816 sc1
	global_load_dword v12, v193, s[58:59] offset:3072 sc1
	global_load_dword v13, v193, s[58:59] offset:3328 sc1
	global_load_dword v14, v193, s[58:59] offset:3584 sc1
	global_load_dword v15, v193, s[58:59] offset:3840 sc1
	s_mov_b64 s[42:43], -1
	s_mov_b64 s[48:49], -1
	s_waitcnt vmcnt(0)
	v_add_u32_e32 v16, v1, v0
	v_add_u32_e32 v16, v16, v2
	v_add_u32_e32 v16, v16, v3
	v_add_u32_e32 v16, v16, v4
	v_add_u32_e32 v16, v16, v5
	v_add_u32_e32 v16, v16, v6
	v_add_u32_e32 v16, v16, v7
	v_add_u32_e32 v16, v16, v8
	v_add_u32_e32 v16, v16, v9
	v_add_u32_e32 v16, v16, v10
	v_add_u32_e32 v16, v16, v11
	v_add_u32_e32 v16, v16, v12
	v_add_u32_e32 v16, v16, v13
	v_add_u32_e32 v16, v16, v14
	v_add_u32_e32 v16, v16, v15
	v_cmp_eq_u32_e32 vcc, s95, v16
	s_cbranch_vccnz .LBB0_94
	s_and_b32 s20, s19, 0xff
	s_cmp_eq_u32 s20, 0
	s_mov_b64 s[50:51], -1
	s_sleep 1
	s_cbranch_scc1 .LBB0_99
	s_and_b64 vcc, exec, s[50:51]
	s_cbranch_vccz .LBB0_94

; __device__ __forceinline__ void moba_unit(const Ctx& C, int unit, const float* KM) {
;     ...
;     {
;         const float* TC = (const float*)(C.ws + WS_TABC) + h * 4096;
;         float tv[8], kv[2]; v4u qv[8];
; #pragma unroll
;         for (int i = 0; i < 8; ++i) { const int d = tid + 512 * i; tv[i] = (d < ndist) ? TC[d] : 0.f; }
; #pragma unroll
;         for (int i = 0; i < 2; ++i) { const int e = tid + 512 * i; kv[i] = (e < qb * 64) ? KM[(size_t)(b * 16 + (e >> 6)) * 512 + h * 64 + (e & 63)] : 0.f; }
.LBB0_398:
	s_or_b64 exec, exec, s[56:57]
	v_readlane_b32 s0, v247, 14
	v_readlane_b32 s1, v247, 15
	s_lshl_b64 s[22:23], s[0:1], 2
	s_add_u32 s24, s64, s22
	s_addc_u32 s23, s65, s23
	s_bfe_u32 s71, s74, 0x30003
	s_lshl_b32 s22, s70, 6
	s_lshl_b32 s21, s71, 4
	s_lshl_b32 s25, s20, 8
	s_add_u32 s24, s24, s25
	s_addc_u32 s25, s23, 0
	v_lshlrev_b32_e32 v192, 2, v169
	v_lshl_add_u64 v[0:1], s[24:25], 0, v[192:193]
	s_mov_b64 s[0:1], 0x40000
	v_lshl_add_u64 v[0:1], v[0:1], 0, s[0:1]
	v_cmp_gt_i32_e64 s[54:55], s22, v132
	v_mov_b32_e32 v44, 0
	v_mov_b32_e32 v45, 0
	s_and_saveexec_b64 s[56:57], s[54:55]
	s_cbranch_execz .LBB0_400
	v_ashrrev_i32_e32 v2, 6, v132
	v_add_u32_e32 v2, s21, v2
	v_ashrrev_i32_e32 v3, 31, v2
	v_lshlrev_b64 v[2:3], 11, v[2:3]
	v_lshl_add_u64 v[2:3], v[0:1], 0, v[2:3]
	global_load_dword v45, v[2:3], off
.LBB0_400:
	s_or_b64 exec, exec, s[56:57]
	v_cmp_gt_i32_e64 s[56:57], s22, v42
	s_and_saveexec_b64 s[66:67], s[56:57]
	s_cbranch_execz .LBB0_402
	v_ashrrev_i32_e32 v2, 6, v42
	v_add_u32_e32 v2, s21, v2
	v_ashrrev_i32_e32 v3, 31, v2
	v_lshlrev_b64 v[2:3], 11, v[2:3]
	v_lshl_add_u64 v[0:1], v[0:1], 0, v[2:3]
	global_load_dword v44, v[0:1], off

; __device__ __forceinline__ void moba_unit(const Ctx& C, int unit, const float* KM) {
;     ...
;         for (int i = 0; i < 8; ++i) { const int d = tid + 512 * i; if (d < ndist) tabC[d] = tv[i]; }
; #pragma unroll
;         for (int i = 0; i < 2; ++i) { const int e = tid + 512 * i; if (e < qb * 64) kml[e] = kv[i] * (1.0f / 256.0f); }
.LBB0_411:
	s_waitcnt vmcnt(8)
	v_add_u32_e32 v35, 0x16000, v46
	v_mul_f32_e32 v45, 0x3b800000, v45
	ds_write_b32 v35, v45
	s_or_b64 exec, exec, s[38:39]
	s_and_saveexec_b64 s[38:39], s[56:57]
	s_cbranch_execnz .LBB0_432

; __device__ __forceinline__ void moba_unit(const Ctx& C, int unit, const float* KM) {
;     ...
;         for (int i = 0; i < 2; ++i) { const int e = tid + 512 * i; if (e < qb * 64) kml[e] = kv[i] * (1.0f / 256.0f); }
;         if (tid < 16) cnt[tid] = 0;
.LBB0_432:
	s_waitcnt vmcnt(8)
	v_lshl_add_u32 v35, v42, 2, 0
	v_add_u32_e32 v35, 0x16000, v35
	v_mul_f32_e32 v44, 0x3b800000, v44
	ds_write_b32 v35, v44
	s_or_b64 exec, exec, s[38:39]
	v_cmp_gt_i32_e32 vcc, 16, v132
	s_and_saveexec_b64 s[38:39], vcc
	s_cbranch_execnz .LBB0_413
	s_branch .LBB0_414

; #define LAS __attribute__((address_space(3)))
; __device__ __forceinline__ f32x4 mfma16(bf16x8 a, bf16x8 b, f32x4 c) { return __builtin_amdgcn_mfma_f32_16x16x32_bf16(a, b, c, 0, 0, 0); }
; #define SBAR() __builtin_amdgcn_sched_barrier(0)
; #define SBAR() __builtin_amdgcn_sched_barrier(0)
; template <bool OWN>
; __device__ __forceinline__ void moba_item(const bf16x8 q0, const bf16x8 q1, LAS unsigned char* lds, int lane, int qb, int n, int qid, bool valid, int smax) {
;     ...
;     f32x4 S[16];
; #pragma unroll
;     for (int sp = 0; sp < 4; ++sp) if (!OWN || 2 * sp <= smax) {
;         bf16x8 kf[4][2];
; #pragma unroll
;         for (int t = 0; t < 4; ++t) { const LAS unsigned char* kp = kbase + (64 * sp + 32 * (t >> 1) + 16 * (t & 1)) * 144; kf[t][0] = *(const LAS bf16x8*)kp; kf[t][1] = *(const LAS bf16x8*)(kp + 64); }
;         SBAR();
; #pragma unroll
;         for (int t = 0; t < 4; ++t) { f32x4 a = mfma16(kf[t][0], q0, (f32x4){0.f, 0.f, 0.f, 0.f}); S[4 * sp + t] = mfma16(kf[t][1], q1, a); }
;         SBAR();
;     }
;     const float c2 = 0.125f * 1.4426950408889634f;
;     const LAS float* tb = (const LAS float*)(lds + MB_TAB) + (256 * (qb - n) + qid - 4 * g - 255);
;     float mx = NEGF;
; #pragma unroll
;     for (int sp = 0; sp < 4; ++sp) if (!OWN || 2 * sp <= smax) {
;         float tv[16];
; #pragma unroll
;         for (int t = 0; t < 4; ++t)
; #pragma unroll
;             for (int jj = 0; jj < 4; ++jj) tv[4 * t + jj] = tb[255 - (64 * sp + 32 * (t >> 1) + 16 * (t & 1) + jj)];
;         SBAR();
; #pragma unroll
;         for (int t = 0; t < 4; ++t)
; #pragma unroll
;             for (int jj = 0; jj < 4; ++jj) {
;                 float v = S[4 * sp + t][jj] * c2 + tv[4 * t + jj];
;                 if (OWN) { const int key = 64 * sp + 32 * (t >> 1) + 16 * (t & 1) + 4 * g + jj; v = (key <= qid) ? v : NEGF; }
;                 S[4 * sp + t][jj] = v; mx = fmaxf(mx, v);
;             }
;     }
.Lmb_w_done:
	s_waitcnt lgkmcnt(7)
	v_mfma_f32_16x16x32_bf16 v[32:35], v[32:35], v[96:99], 0
	s_waitcnt lgkmcnt(6)
	v_mfma_f32_16x16x32_bf16 v[82:85], v[36:39], v[100:103], v[32:35]
	s_waitcnt lgkmcnt(5)
	v_mfma_f32_16x16x32_bf16 v[32:35], v[40:43], v[96:99], 0
	s_waitcnt lgkmcnt(4)
	v_mfma_f32_16x16x32_bf16 v[86:89], v[44:47], v[100:103], v[32:35]
	s_waitcnt lgkmcnt(3)
	v_mfma_f32_16x16x32_bf16 v[32:35], v[48:51], v[96:99], 0
	s_waitcnt lgkmcnt(2)
	v_mfma_f32_16x16x32_bf16 v[90:93], v[52:55], v[100:103], v[32:35]
	s_waitcnt lgkmcnt(1)
	v_mfma_f32_16x16x32_bf16 v[32:35], v[56:59], v[96:99], 0
	s_waitcnt lgkmcnt(0)
	v_mfma_f32_16x16x32_bf16 v[170:173], v[60:63], v[100:103], v[32:35]
	s_nop 5
	ds_read_b128 v[32:35], v218 offset:9216
	ds_read_b128 v[36:39], v218 offset:9280
	ds_read_b128 v[40:43], v218 offset:11520
	ds_read_b128 v[44:47], v218 offset:11584
	ds_read_b128 v[48:51], v218 offset:13824
	ds_read_b128 v[52:55], v218 offset:13888
	ds_read_b128 v[56:59], v218 offset:16128
	ds_read_b128 v[60:63], v218 offset:16192
	s_waitcnt lgkmcnt(7)
	v_mfma_f32_16x16x32_bf16 v[32:35], v[32:35], v[96:99], 0
	s_waitcnt lgkmcnt(6)
	v_mfma_f32_16x16x32_bf16 v[174:177], v[36:39], v[100:103], v[32:35]
	s_waitcnt lgkmcnt(5)
	v_mfma_f32_16x16x32_bf16 v[32:35], v[40:43], v[96:99], 0
	s_waitcnt lgkmcnt(4)
	v_mfma_f32_16x16x32_bf16 v[178:181], v[44:47], v[100:103], v[32:35]
	s_waitcnt lgkmcnt(3)
	v_mfma_f32_16x16x32_bf16 v[32:35], v[48:51], v[96:99], 0
	s_waitcnt lgkmcnt(2)
	v_mfma_f32_16x16x32_bf16 v[182:185], v[52:55], v[100:103], v[32:35]
	s_waitcnt lgkmcnt(1)
	v_mfma_f32_16x16x32_bf16 v[32:35], v[56:59], v[96:99], 0
	s_waitcnt lgkmcnt(0)
	v_mfma_f32_16x16x32_bf16 v[224:227], v[60:63], v[100:103], v[32:35]
	s_nop 5
	ds_read_b128 v[32:35], v218 offset:18432
	ds_read_b128 v[36:39], v218 offset:18496
	ds_read_b128 v[40:43], v218 offset:20736
	ds_read_b128 v[44:47], v218 offset:20800
	ds_read_b128 v[48:51], v218 offset:23040
	ds_read_b128 v[52:55], v218 offset:23104
	ds_read_b128 v[64:67], v218 offset:25344
	ds_read_b128 v[68:71], v218 offset:25408
	s_waitcnt lgkmcnt(7)
	v_mfma_f32_16x16x32_bf16 v[32:35], v[32:35], v[96:99], 0
	s_waitcnt lgkmcnt(6)
	v_mfma_f32_16x16x32_bf16 v[60:63], v[36:39], v[100:103], v[32:35]
	s_waitcnt lgkmcnt(5)
	v_mfma_f32_16x16x32_bf16 v[32:35], v[40:43], v[96:99], 0
	s_waitcnt lgkmcnt(4)
	v_mfma_f32_16x16x32_bf16 v[56:59], v[44:47], v[100:103], v[32:35]
	s_waitcnt lgkmcnt(3)
	v_mfma_f32_16x16x32_bf16 v[32:35], v[48:51], v[96:99], 0
	s_waitcnt lgkmcnt(2)
	v_mfma_f32_16x16x32_bf16 v[52:55], v[52:55], v[100:103], v[32:35]
	s_waitcnt lgkmcnt(1)
	v_mfma_f32_16x16x32_bf16 v[32:35], v[64:67], v[96:99], 0
	s_waitcnt lgkmcnt(0)
	v_mfma_f32_16x16x32_bf16 v[48:51], v[68:71], v[100:103], v[32:35]
	s_nop 5
	ds_read_b128 v[32:35], v218 offset:27648
	ds_read_b128 v[36:39], v218 offset:27712
	ds_read_b128 v[40:43], v218 offset:29952
	ds_read_b128 v[64:67], v218 offset:30016
	ds_read_b128 v[68:71], v218 offset:32256
	ds_read_b128 v[72:75], v218 offset:32320
	ds_read_b128 v[76:79], v218 offset:34560
	ds_read_b128 v[238:241], v218 offset:34624
	s_waitcnt lgkmcnt(7)
	v_mfma_f32_16x16x32_bf16 v[32:35], v[32:35], v[96:99], 0
	s_waitcnt lgkmcnt(6)
	v_mfma_f32_16x16x32_bf16 v[44:47], v[36:39], v[100:103], v[32:35]
	s_waitcnt lgkmcnt(5)
	v_mfma_f32_16x16x32_bf16 v[32:35], v[40:43], v[96:99], 0
	s_waitcnt lgkmcnt(4)
	v_mfma_f32_16x16x32_bf16 v[40:43], v[64:67], v[100:103], v[32:35]
	s_waitcnt lgkmcnt(3)
	v_mfma_f32_16x16x32_bf16 v[32:35], v[68:71], v[96:99], 0
	s_waitcnt lgkmcnt(2)
	v_mfma_f32_16x16x32_bf16 v[36:39], v[72:75], v[100:103], v[32:35]
	s_waitcnt lgkmcnt(1)
	v_mfma_f32_16x16x32_bf16 v[32:35], v[76:79], v[96:99], 0
	s_waitcnt lgkmcnt(0)
	v_mfma_f32_16x16x32_bf16 v[32:35], v[238:241], v[100:103], v[32:35]
	v_lshl_add_u32 v223, v222, 2, s21
	v_add_u32_e32 v64, 0x5ffc, v223
	v_add_u32_e32 v65, 0x5ff4, v223
	v_add_u32_e32 v66, 0x5fbc, v223
	v_add_u32_e32 v67, 0x5fb4, v223
	ds_read2_b32 v[80:81], v64 offset1:1
	ds_read2_b32 v[76:77], v65 offset1:1
	ds_read2_b32 v[74:75], v66 offset1:1
	ds_read2_b32 v[72:73], v67 offset1:1
	v_add_u32_e32 v64, 0x5f7c, v223
	v_add_u32_e32 v65, 0x5f74, v223
	v_add_u32_e32 v66, 0x5f3c, v223
	v_add_u32_e32 v78, 0x5f34, v223
	ds_read2_b32 v[70:71], v64 offset1:1
	ds_read2_b32 v[68:69], v65 offset1:1
	ds_read2_b32 v[66:67], v66 offset1:1
	ds_read2_b32 v[64:65], v78 offset1:1
	s_waitcnt lgkmcnt(7)
	v_fmamk_f32 v81, v82, 0x3e38aa3b, v81
	v_fmac_f32_e32 v80, 0x3e38aa3b, v83
	v_max3_f32 v78, v81, s17, v80
	s_waitcnt lgkmcnt(6)
	v_fmamk_f32 v77, v84, 0x3e38aa3b, v77
	v_fmac_f32_e32 v76, 0x3e38aa3b, v85
	v_max3_f32 v78, v78, v77, v76
	s_waitcnt lgkmcnt(5)
	v_fmamk_f32 v75, v86, 0x3e38aa3b, v75
	v_fmac_f32_e32 v74, 0x3e38aa3b, v87
	v_max3_f32 v78, v78, v75, v74
	s_waitcnt lgkmcnt(4)
	v_fmamk_f32 v73, v88, 0x3e38aa3b, v73
	v_fmac_f32_e32 v72, 0x3e38aa3b, v89
	v_max3_f32 v78, v78, v73, v72
	s_waitcnt lgkmcnt(3)
	v_fmamk_f32 v71, v90, 0x3e38aa3b, v71
	v_fmac_f32_e32 v70, 0x3e38aa3b, v91
	v_max3_f32 v78, v78, v71, v70
	s_waitcnt lgkmcnt(2)
	v_fmamk_f32 v69, v92, 0x3e38aa3b, v69
	v_fmac_f32_e32 v68, 0x3e38aa3b, v93
	v_max3_f32 v78, v78, v69, v68
	s_waitcnt lgkmcnt(1)
	v_fmamk_f32 v67, v170, 0x3e38aa3b, v67
	v_fmac_f32_e32 v66, 0x3e38aa3b, v171
	v_max3_f32 v78, v78, v67, v66
	s_waitcnt lgkmcnt(0)
; #define SBAR() __builtin_amdgcn_sched_barrier(0)
; #define SBAR() __builtin_amdgcn_sched_barrier(0)
; template <bool OWN>
; __device__ __forceinline__ void moba_item(const bf16x8 q0, const bf16x8 q1, LAS unsigned char* lds, int lane, int qb, int n, int qid, bool valid, int smax) {
;     ...
;     for (int sp = 0; sp < 4; ++sp) if (!OWN || 2 * sp <= smax) {
;         float tv[16];
; #pragma unroll
;         for (int t = 0; t < 4; ++t)
; #pragma unroll
;             for (int jj = 0; jj < 4; ++jj) tv[4 * t + jj] = tb[255 - (64 * sp + 32 * (t >> 1) + 16 * (t & 1) + jj)];
;         SBAR();
; #pragma unroll
;         for (int t = 0; t < 4; ++t)
; #pragma unroll
;             for (int jj = 0; jj < 4; ++jj) {
;                 float v = S[4 * sp + t][jj] * c2 + tv[4 * t + jj];
;                 if (OWN) { const int key = 64 * sp + 32 * (t >> 1) + 16 * (t & 1) + 4 * g + jj; v = (key <= qid) ? v : NEGF; }
;                 S[4 * sp + t][jj] = v; mx = fmaxf(mx, v);
;             }
;     }
	v_fmamk_f32 v65, v172, 0x3e38aa3b, v65
	v_fmac_f32_e32 v64, 0x3e38aa3b, v173
	v_max3_f32 v170, v78, v65, v64
	v_add_u32_e32 v78, 0x5efc, v223
	v_add_u32_e32 v90, 0x5e34, v223
	ds_read2_b32 v[92:93], v78 offset1:1
	ds_read2_b32 v[90:91], v90 offset1:1
	v_add_u32_e32 v78, 0x5ef4, v223
	ds_read2_b32 v[88:89], v78 offset1:1
	v_add_u32_e32 v78, 0x5ebc, v223
	ds_read2_b32 v[82:83], v78 offset1:1
	v_add_u32_e32 v78, 0x5eb4, v223
	ds_read2_b32 v[94:95], v78 offset1:1
	v_add_u32_e32 v78, 0x5e7c, v223
	ds_read2_b32 v[86:87], v78 offset1:1
	v_add_u32_e32 v78, 0x5e74, v223
	ds_read2_b32 v[84:85], v78 offset1:1
	v_add_u32_e32 v78, 0x5e3c, v223
	ds_read2_b32 v[78:79], v78 offset1:1
	s_waitcnt lgkmcnt(7)
	v_fmamk_f32 v93, v174, 0x3e38aa3b, v93
	v_fmac_f32_e32 v92, 0x3e38aa3b, v175
	v_max3_f32 v170, v170, v93, v92
	s_waitcnt lgkmcnt(5)
	v_fmamk_f32 v89, v176, 0x3e38aa3b, v89
	v_fmac_f32_e32 v88, 0x3e38aa3b, v177
	v_max3_f32 v170, v170, v89, v88
	s_waitcnt lgkmcnt(4)
	v_fmamk_f32 v83, v178, 0x3e38aa3b, v83
	v_fmac_f32_e32 v82, 0x3e38aa3b, v179
	v_max3_f32 v170, v170, v83, v82
	s_waitcnt lgkmcnt(3)
	v_fmamk_f32 v95, v180, 0x3e38aa3b, v95
	v_fmac_f32_e32 v94, 0x3e38aa3b, v181
	v_max3_f32 v170, v170, v95, v94
	s_waitcnt lgkmcnt(2)
	v_fmamk_f32 v87, v182, 0x3e38aa3b, v87
	v_fmac_f32_e32 v86, 0x3e38aa3b, v183
	v_max3_f32 v170, v170, v87, v86
	s_waitcnt lgkmcnt(1)
	v_fmamk_f32 v85, v184, 0x3e38aa3b, v85
	v_fmac_f32_e32 v84, 0x3e38aa3b, v185
	v_max3_f32 v170, v170, v85, v84
	s_waitcnt lgkmcnt(0)
	v_fmamk_f32 v79, v224, 0x3e38aa3b, v79
	v_fmac_f32_e32 v78, 0x3e38aa3b, v225
	v_max3_f32 v170, v170, v79, v78
	v_fmamk_f32 v91, v226, 0x3e38aa3b, v91
	v_fmac_f32_e32 v90, 0x3e38aa3b, v227
	v_max3_f32 v224, v170, v91, v90
	v_add_u32_e32 v170, 0x5dfc, v223
	v_add_u32_e32 v180, 0x5d34, v223
	ds_read2_b32 v[182:183], v170 offset1:1
	ds_read2_b32 v[180:181], v180 offset1:1
	v_add_u32_e32 v170, 0x5df4, v223
	ds_read2_b32 v[178:179], v170 offset1:1
	v_add_u32_e32 v170, 0x5dbc, v223
	ds_read2_b32 v[172:173], v170 offset1:1
	v_add_u32_e32 v170, 0x5db4, v223
	ds_read2_b32 v[184:185], v170 offset1:1
	v_add_u32_e32 v170, 0x5d7c, v223
	ds_read2_b32 v[176:177], v170 offset1:1
	v_add_u32_e32 v170, 0x5d74, v223
	ds_read2_b32 v[174:175], v170 offset1:1
	v_add_u32_e32 v170, 0x5d3c, v223
	ds_read2_b32 v[170:171], v170 offset1:1
	s_waitcnt lgkmcnt(7)
	v_fmamk_f32 v183, v60, 0x3e38aa3b, v183
	v_fmac_f32_e32 v182, 0x3e38aa3b, v61
	v_max3_f32 v60, v224, v183, v182
	s_waitcnt lgkmcnt(5)
	v_fmamk_f32 v179, v62, 0x3e38aa3b, v179
	v_fmac_f32_e32 v178, 0x3e38aa3b, v63
	v_max3_f32 v60, v60, v179, v178
	s_waitcnt lgkmcnt(4)
	v_fmamk_f32 v173, v56, 0x3e38aa3b, v173
	v_fmac_f32_e32 v172, 0x3e38aa3b, v57
	v_max3_f32 v56, v60, v173, v172
	s_waitcnt lgkmcnt(3)
	v_fmamk_f32 v185, v58, 0x3e38aa3b, v185
	v_fmac_f32_e32 v184, 0x3e38aa3b, v59
	v_max3_f32 v56, v56, v185, v184
	s_waitcnt lgkmcnt(2)
	v_fmamk_f32 v177, v52, 0x3e38aa3b, v177
	v_fmac_f32_e32 v176, 0x3e38aa3b, v53
	v_max3_f32 v52, v56, v177, v176
	s_waitcnt lgkmcnt(1)
	v_fmamk_f32 v175, v54, 0x3e38aa3b, v175
	v_fmac_f32_e32 v174, 0x3e38aa3b, v55
	v_max3_f32 v52, v52, v175, v174
	s_waitcnt lgkmcnt(0)
	v_fmamk_f32 v171, v48, 0x3e38aa3b, v171
	v_fmac_f32_e32 v170, 0x3e38aa3b, v49
	v_max3_f32 v48, v52, v171, v170
	v_fmamk_f32 v181, v50, 0x3e38aa3b, v181
	v_fmac_f32_e32 v180, 0x3e38aa3b, v51
	v_max3_f32 v224, v48, v181, v180
	v_add_u32_e32 v48, 0x5cfc, v223
	v_add_u32_e32 v58, 0x5c34, v223
	ds_read2_b32 v[60:61], v48 offset1:1
	ds_read2_b32 v[58:59], v58 offset1:1
	v_add_u32_e32 v48, 0x5cf4, v223
	ds_read2_b32 v[56:57], v48 offset1:1
	v_add_u32_e32 v48, 0x5cbc, v223
	ds_read2_b32 v[50:51], v48 offset1:1
	v_add_u32_e32 v48, 0x5cb4, v223
	ds_read2_b32 v[62:63], v48 offset1:1
	v_add_u32_e32 v48, 0x5c7c, v223
	ds_read2_b32 v[54:55], v48 offset1:1
	v_add_u32_e32 v48, 0x5c74, v223
	ds_read2_b32 v[52:53], v48 offset1:1
	v_add_u32_e32 v48, 0x5c3c, v223
	ds_read2_b32 v[48:49], v48 offset1:1
	s_waitcnt lgkmcnt(7)
	v_fmamk_f32 v44, v44, 0x3e38aa3b, v61
	v_fmac_f32_e32 v60, 0x3e38aa3b, v45
	v_max3_f32 v45, v224, v44, v60
	s_waitcnt lgkmcnt(5)
	v_fmamk_f32 v46, v46, 0x3e38aa3b, v57
	v_fmac_f32_e32 v56, 0x3e38aa3b, v47
	v_max3_f32 v45, v45, v46, v56
	s_waitcnt lgkmcnt(4)
	v_fmamk_f32 v40, v40, 0x3e38aa3b, v51
	v_fmac_f32_e32 v50, 0x3e38aa3b, v41
	v_max3_f32 v41, v45, v40, v50
	s_waitcnt lgkmcnt(3)
	v_fmamk_f32 v42, v42, 0x3e38aa3b, v63
	v_fmac_f32_e32 v62, 0x3e38aa3b, v43
	v_max3_f32 v41, v41, v42, v62
	s_waitcnt lgkmcnt(2)
	v_fmamk_f32 v36, v36, 0x3e38aa3b, v55
	v_fmac_f32_e32 v54, 0x3e38aa3b, v37
	v_max3_f32 v37, v41, v36, v54
	s_waitcnt lgkmcnt(1)
	v_fmamk_f32 v38, v38, 0x3e38aa3b, v53
	v_fmac_f32_e32 v52, 0x3e38aa3b, v39
	v_max3_f32 v37, v37, v38, v52
	s_waitcnt lgkmcnt(0)
; template <bool OWN>
; __device__ __forceinline__ void moba_item(const bf16x8 q0, const bf16x8 q1, LAS unsigned char* lds, int lane, int qb, int n, int qid, bool valid, int smax) {
;     ...
;     mx = fmaxf(mx, __shfl_xor(mx, 16)); mx = fmaxf(mx, __shfl_xor(mx, 32));
;     float sum = 0.f;
; #pragma unroll
;     for (int sp = 0; sp < 4; ++sp) if (!OWN || 2 * sp <= smax) {
; #pragma unroll
;         for (int t = 0; t < 4; ++t)
; #pragma unroll
;             for (int jj = 0; jj < 4; ++jj) { const float pv = __builtin_amdgcn_exp2f(S[4 * sp + t][jj] - mx); S[4 * sp + t][jj] = pv; sum += pv; }
;     }
;     sum += __shfl_xor(sum, 16); sum += __shfl_xor(sum, 32);
	v_fmamk_f32 v32, v32, 0x3e38aa3b, v49
	v_fmac_f32_e32 v48, 0x3e38aa3b, v33
	v_max3_f32 v33, v37, v32, v48
	v_fmac_f32_e32 v58, 0x3e38aa3b, v35
	v_fmamk_f32 v34, v34, 0x3e38aa3b, v59
	v_max3_f32 v33, v33, v34, v58
	v_mov_b32_e32 v39, v33
	s_nop 1
	v_permlane16_swap_b32_e32 v33, v39
	v_max_f32_e32 v33, v33, v39
	v_mov_b32_e32 v39, v33
	s_nop 1
	v_permlane32_swap_b32_e32 v33, v39
	v_max_f32_e32 v51, v33, v39
	v_sub_f32_e32 v33, v81, v51
	v_exp_f32_e32 v49, v33
	v_sub_f32_e32 v33, v80, v51
	v_exp_f32_e32 v55, v33
	v_sub_f32_e32 v33, v77, v51
	v_exp_f32_e32 v57, v33
	v_sub_f32_e32 v33, v76, v51
	v_exp_f32_e32 v59, v33
	v_sub_f32_e32 v39, v75, v51
	v_add_f32_e32 v33, 0, v49
	v_exp_f32_e32 v61, v39
	v_sub_f32_e32 v39, v74, v51
	v_add_f32_e32 v33, v55, v33
	v_exp_f32_e32 v63, v39
	v_sub_f32_e32 v39, v73, v51
	v_add_f32_e32 v33, v57, v33
	v_exp_f32_e32 v73, v39
	v_sub_f32_e32 v39, v72, v51
	v_add_f32_e32 v33, v59, v33
	v_exp_f32_e32 v72, v39
	v_sub_f32_e32 v39, v71, v51
	v_add_f32_e32 v33, v61, v33
	v_exp_f32_e32 v71, v39
	v_sub_f32_e32 v39, v70, v51
	v_add_f32_e32 v33, v63, v33
	v_exp_f32_e32 v70, v39
	v_sub_f32_e32 v39, v69, v51
	v_add_f32_e32 v33, v73, v33
	v_exp_f32_e32 v74, v39
	v_sub_f32_e32 v39, v68, v51
	v_add_f32_e32 v33, v72, v33
	v_exp_f32_e32 v75, v39
	v_sub_f32_e32 v39, v67, v51
	v_add_f32_e32 v33, v71, v33
	v_exp_f32_e32 v76, v39
	v_sub_f32_e32 v39, v66, v51
	v_add_f32_e32 v33, v70, v33
	v_exp_f32_e32 v77, v39
	v_sub_f32_e32 v39, v65, v51
	v_add_f32_e32 v33, v74, v33
	v_exp_f32_e32 v80, v39
	v_sub_f32_e32 v39, v64, v51
	v_add_f32_e32 v33, v75, v33
	v_exp_f32_e32 v81, v39
	v_sub_f32_e32 v39, v93, v51
	v_add_f32_e32 v33, v76, v33
	v_exp_f32_e32 v93, v39
	v_sub_f32_e32 v39, v92, v51
	v_add_f32_e32 v33, v77, v33
	v_exp_f32_e32 v92, v39
	v_sub_f32_e32 v39, v89, v51
	v_add_f32_e32 v33, v80, v33
	v_exp_f32_e32 v89, v39
	v_sub_f32_e32 v39, v88, v51
	v_add_f32_e32 v33, v81, v33
	v_exp_f32_e32 v88, v39
	v_sub_f32_e32 v39, v83, v51
	v_add_f32_e32 v33, v93, v33
	v_exp_f32_e32 v83, v39
	v_sub_f32_e32 v39, v82, v51
	v_add_f32_e32 v33, v92, v33
	v_exp_f32_e32 v82, v39
	v_sub_f32_e32 v39, v95, v51
	v_add_f32_e32 v33, v89, v33
	v_exp_f32_e32 v95, v39
	v_sub_f32_e32 v39, v94, v51
	v_add_f32_e32 v33, v88, v33
	v_exp_f32_e32 v94, v39
	v_sub_f32_e32 v39, v87, v51
	v_add_f32_e32 v33, v83, v33
	v_exp_f32_e32 v87, v39
	v_sub_f32_e32 v39, v86, v51
	v_add_f32_e32 v33, v82, v33
	v_exp_f32_e32 v86, v39
	v_sub_f32_e32 v39, v85, v51
	v_add_f32_e32 v33, v95, v33
	v_exp_f32_e32 v85, v39
	v_sub_f32_e32 v39, v84, v51
	v_add_f32_e32 v33, v94, v33
	v_exp_f32_e32 v84, v39
	v_sub_f32_e32 v39, v79, v51
	v_add_f32_e32 v33, v87, v33
	v_exp_f32_e32 v79, v39
	v_sub_f32_e32 v39, v78, v51
	v_add_f32_e32 v33, v86, v33
	v_exp_f32_e32 v78, v39
	v_sub_f32_e32 v39, v91, v51
	v_add_f32_e32 v33, v85, v33
	v_exp_f32_e32 v91, v39
	v_sub_f32_e32 v39, v90, v51
	v_add_f32_e32 v33, v84, v33
	v_exp_f32_e32 v90, v39
	v_sub_f32_e32 v39, v183, v51
	v_add_f32_e32 v33, v79, v33
	v_exp_f32_e32 v183, v39
	v_sub_f32_e32 v39, v182, v51
	v_add_f32_e32 v33, v78, v33
	v_exp_f32_e32 v182, v39
	v_sub_f32_e32 v39, v179, v51
	v_add_f32_e32 v33, v91, v33
	v_exp_f32_e32 v179, v39
	v_sub_f32_e32 v39, v178, v51
	v_add_f32_e32 v33, v90, v33
	v_exp_f32_e32 v178, v39
	v_sub_f32_e32 v39, v173, v51
	v_add_f32_e32 v33, v183, v33
	v_exp_f32_e32 v173, v39
	v_sub_f32_e32 v39, v172, v51
	v_add_f32_e32 v33, v182, v33
	v_exp_f32_e32 v172, v39
	v_sub_f32_e32 v39, v185, v51
	v_add_f32_e32 v33, v179, v33
	v_exp_f32_e32 v185, v39
	v_sub_f32_e32 v39, v184, v51
	v_add_f32_e32 v33, v178, v33
	v_exp_f32_e32 v184, v39
	v_sub_f32_e32 v39, v177, v51
	v_add_f32_e32 v33, v173, v33
	v_exp_f32_e32 v177, v39
	v_sub_f32_e32 v39, v176, v51
	v_add_f32_e32 v33, v172, v33
	v_exp_f32_e32 v176, v39
	v_sub_f32_e32 v39, v175, v51
	v_add_f32_e32 v33, v185, v33
	v_exp_f32_e32 v175, v39
	v_sub_f32_e32 v39, v174, v51
	v_add_f32_e32 v33, v184, v33
	v_exp_f32_e32 v174, v39
	v_sub_f32_e32 v39, v171, v51
	v_add_f32_e32 v33, v177, v33
	v_exp_f32_e32 v171, v39
	v_sub_f32_e32 v39, v170, v51
	v_add_f32_e32 v33, v176, v33
	v_exp_f32_e32 v170, v39
	v_sub_f32_e32 v39, v181, v51
	v_add_f32_e32 v33, v175, v33
	v_exp_f32_e32 v181, v39
	v_sub_f32_e32 v39, v180, v51
	v_add_f32_e32 v33, v174, v33
	v_exp_f32_e32 v180, v39
	v_sub_f32_e32 v39, v44, v51
	v_add_f32_e32 v33, v171, v33
	v_exp_f32_e32 v223, v39
	v_sub_f32_e32 v39, v60, v51
	v_add_f32_e32 v33, v170, v33
	v_exp_f32_e32 v224, v39
	v_sub_f32_e32 v39, v46, v51
	v_add_f32_e32 v33, v181, v33
	v_exp_f32_e32 v225, v39
	v_sub_f32_e32 v39, v56, v51
	v_add_f32_e32 v33, v180, v33
	v_exp_f32_e32 v226, v39
	v_sub_f32_e32 v39, v40, v51
	v_add_f32_e32 v33, v223, v33
	v_exp_f32_e32 v227, v39
	v_sub_f32_e32 v39, v50, v51
	v_add_f32_e32 v33, v224, v33
	v_exp_f32_e32 v50, v39
	v_sub_f32_e32 v39, v42, v51
	v_add_f32_e32 v33, v225, v33
	v_exp_f32_e32 v238, v39
	v_sub_f32_e32 v39, v62, v51
	v_add_f32_e32 v33, v226, v33
	v_exp_f32_e32 v239, v39
	v_sub_f32_e32 v36, v36, v51
	v_add_f32_e32 v33, v227, v33
	v_exp_f32_e32 v240, v36
	v_sub_f32_e32 v36, v54, v51
	v_add_f32_e32 v33, v50, v33
	v_exp_f32_e32 v241, v36
	v_sub_f32_e32 v36, v38, v51
	v_add_f32_e32 v33, v238, v33
	v_exp_f32_e32 v242, v36
	v_sub_f32_e32 v36, v52, v51
	v_add_f32_e32 v33, v239, v33
	v_exp_f32_e32 v243, v36
	v_sub_f32_e32 v32, v32, v51
	v_add_f32_e32 v33, v240, v33
	v_exp_f32_e32 v244, v32
	v_sub_f32_e32 v32, v48, v51
	v_add_f32_e32 v33, v241, v33
	v_exp_f32_e32 v48, v32
	v_sub_f32_e32 v32, v34, v51
	v_add_f32_e32 v33, v242, v33
	v_exp_f32_e32 v245, v32
	v_sub_f32_e32 v32, v58, v51
	v_add_f32_e32 v33, v243, v33
	v_exp_f32_e32 v246, v32
	v_add_f32_e32 v32, v244, v33
	v_add_f32_e32 v32, v48, v32
	v_add_f32_e32 v32, v245, v32
	v_add_f32_e32 v32, v246, v32
	v_mov_b32_e32 v33, v32
	s_nop 1
	v_permlane16_swap_b32_e32 v32, v33
	v_cvt_pk_bf16_f32 v54, v49, v55
	v_cvt_pk_bf16_f32 v55, v57, v59
	v_cvt_pk_bf16_f32 v56, v61, v63
	v_cvt_pk_bf16_f32 v57, v73, v72
	s_waitcnt lgkmcnt(0)
; #define LAS __attribute__((address_space(3)))
; __device__ __forceinline__ unsigned pk2(float lo, float hi) { f32x2_t v = {lo, hi}; bf16x2_t b = __builtin_convertvector(v, bf16x2_t); return __builtin_bit_cast(unsigned, b); }
; __device__ __forceinline__ f32x4 mfma16(bf16x8 a, bf16x8 b, f32x4 c) { return __builtin_amdgcn_mfma_f32_16x16x32_bf16(a, b, c, 0, 0, 0); }
; __device__ __forceinline__ s16x4 vtr(const LAS unsigned char* p) { return __builtin_bit_cast(s16x4, __builtin_amdgcn_ds_read_tr16_b64_v4i16((LAS s16x4*)p)); }
; #define SBAR() __builtin_amdgcn_sched_barrier(0)
; #define SBAR() __builtin_amdgcn_sched_barrier(0)
; template <bool OWN>
; __device__ __forceinline__ void moba_item(const bf16x8 q0, const bf16x8 q1, LAS unsigned char* lds, int lane, int qb, int n, int qid, bool valid, int smax) {
;     ...
;     sum += __shfl_xor(sum, 16); sum += __shfl_xor(sum, 32);
;     f32x4 O[4];
; #pragma unroll
;     for (int c = 0; c < 4; ++c) O[c] = (f32x4){0.f, 0.f, 0.f, 0.f};
; #pragma unroll
;     for (int s8 = 0; s8 < 8; ++s8) if (!OWN || (s8 >> 1) * 2 <= smax) {
;         s16x4 vl[4][2];
; #pragma unroll
;         for (int c = 0; c < 4; ++c) { const LAS unsigned char* vp = vbase + (32 * s8) * 144 + 32 * c; vl[c][0] = vtr(vp); vl[c][1] = vtr(vp + 16 * 144); }
;         const int t0 = 2 * s8; v4u pw; pw.x = pk2(S[t0][0], S[t0][1]); pw.y = pk2(S[t0][2], S[t0][3]); pw.z = pk2(S[t0 + 1][0], S[t0 + 1][1]); pw.w = pk2(S[t0 + 1][2], S[t0 + 1][3]);
;         const bf16x8 pb = __builtin_bit_cast(bf16x8, pw);
;         SBAR();
; #pragma unroll
;         for (int c = 0; c < 4; ++c) { const s16x4 lo = vl[c][0], hi = vl[c][1];
;             const bf16x8 vf = (bf16x8){lo[0], lo[1], lo[2], lo[3], hi[0], hi[1], hi[2], hi[3]};
;             O[c] = mfma16(vf, pb, O[c]); }
;         SBAR();
;     }
	v_add_f32_e32 v52, v32, v33
	v_mov_b32_e32 v53, v52
	s_nop 1
	v_permlane32_swap_b32_e32 v52, v53
	ds_read_b64_tr_b16 v[32:33], v209
	ds_read_b64_tr_b16 v[36:37], v209 offset:32
	ds_read_b64_tr_b16 v[40:41], v209 offset:64
	ds_read_b64_tr_b16 v[44:45], v209 offset:96
	ds_read_b64_tr_b16 v[34:35], v209 offset:2304
	ds_read_b64_tr_b16 v[38:39], v209 offset:2336
	ds_read_b64_tr_b16 v[42:43], v209 offset:2368
	ds_read_b64_tr_b16 v[46:47], v209 offset:2400
	s_waitcnt lgkmcnt(3)
	v_mfma_f32_16x16x32_bf16 v[32:35], v[32:35], v[54:57], 0
	s_waitcnt lgkmcnt(2)
	v_mfma_f32_16x16x32_bf16 v[36:39], v[36:39], v[54:57], 0
	s_waitcnt lgkmcnt(1)
	v_mfma_f32_16x16x32_bf16 v[40:43], v[40:43], v[54:57], 0
	s_waitcnt lgkmcnt(0)
	v_mfma_f32_16x16x32_bf16 v[44:47], v[44:47], v[54:57], 0
	ds_read_b64_tr_b16 v[54:55], v209 offset:4608
	ds_read_b64_tr_b16 v[58:59], v209 offset:4640
	ds_read_b64_tr_b16 v[62:63], v209 offset:4672
	ds_read_b64_tr_b16 v[66:67], v209 offset:4704
	ds_read_b64_tr_b16 v[56:57], v209 offset:6912
	ds_read_b64_tr_b16 v[60:61], v209 offset:6944
	ds_read_b64_tr_b16 v[64:65], v209 offset:6976
	ds_read_b64_tr_b16 v[68:69], v209 offset:7008
	v_cvt_pk_bf16_f32 v70, v71, v70
	v_cvt_pk_bf16_f32 v71, v74, v75
	v_cvt_pk_bf16_f32 v72, v76, v77
	v_cvt_pk_bf16_f32 v73, v80, v81
	s_waitcnt lgkmcnt(3)
	s_nop 0
	v_mfma_f32_16x16x32_bf16 v[32:35], v[54:57], v[70:73], v[32:35]
	s_waitcnt lgkmcnt(2)
	v_mfma_f32_16x16x32_bf16 v[36:39], v[58:61], v[70:73], v[36:39]
	s_waitcnt lgkmcnt(1)
	v_mfma_f32_16x16x32_bf16 v[40:43], v[62:65], v[70:73], v[40:43]
	s_waitcnt lgkmcnt(0)
	v_mfma_f32_16x16x32_bf16 v[44:47], v[66:69], v[70:73], v[44:47]
	ds_read_b64_tr_b16 v[54:55], v209 offset:9216
	ds_read_b64_tr_b16 v[58:59], v209 offset:9248
	ds_read_b64_tr_b16 v[62:63], v209 offset:9280
	ds_read_b64_tr_b16 v[66:67], v209 offset:9312
	ds_read_b64_tr_b16 v[56:57], v209 offset:11520
	ds_read_b64_tr_b16 v[60:61], v209 offset:11552
	ds_read_b64_tr_b16 v[64:65], v209 offset:11584
	ds_read_b64_tr_b16 v[68:69], v209 offset:11616
	v_cvt_pk_bf16_f32 v70, v93, v92
	v_cvt_pk_bf16_f32 v71, v89, v88
	v_cvt_pk_bf16_f32 v72, v83, v82
	v_cvt_pk_bf16_f32 v73, v95, v94
	s_waitcnt lgkmcnt(3)
	s_nop 0
	v_mfma_f32_16x16x32_bf16 v[32:35], v[54:57], v[70:73], v[32:35]
	s_waitcnt lgkmcnt(2)
	v_mfma_f32_16x16x32_bf16 v[36:39], v[58:61], v[70:73], v[36:39]
	s_waitcnt lgkmcnt(1)
	v_mfma_f32_16x16x32_bf16 v[40:43], v[62:65], v[70:73], v[40:43]
	s_waitcnt lgkmcnt(0)
	v_mfma_f32_16x16x32_bf16 v[44:47], v[66:69], v[70:73], v[44:47]
	ds_read_b64_tr_b16 v[54:55], v209 offset:13824
	ds_read_b64_tr_b16 v[58:59], v209 offset:13856
	ds_read_b64_tr_b16 v[62:63], v209 offset:13888
	ds_read_b64_tr_b16 v[66:67], v209 offset:13920
	ds_read_b64_tr_b16 v[56:57], v209 offset:16128
	ds_read_b64_tr_b16 v[60:61], v209 offset:16160
	ds_read_b64_tr_b16 v[64:65], v209 offset:16192
	ds_read_b64_tr_b16 v[68:69], v209 offset:16224
	v_cvt_pk_bf16_f32 v70, v87, v86
	v_cvt_pk_bf16_f32 v71, v85, v84
	v_cvt_pk_bf16_f32 v72, v79, v78
	v_cvt_pk_bf16_f32 v73, v91, v90
	s_waitcnt lgkmcnt(3)
	s_nop 0
	v_mfma_f32_16x16x32_bf16 v[32:35], v[54:57], v[70:73], v[32:35]
	s_waitcnt lgkmcnt(2)
	v_mfma_f32_16x16x32_bf16 v[36:39], v[58:61], v[70:73], v[36:39]
	s_waitcnt lgkmcnt(1)
	v_mfma_f32_16x16x32_bf16 v[40:43], v[62:65], v[70:73], v[40:43]
	s_waitcnt lgkmcnt(0)
	v_mfma_f32_16x16x32_bf16 v[44:47], v[66:69], v[70:73], v[44:47]
	ds_read_b64_tr_b16 v[54:55], v209 offset:18432
	ds_read_b64_tr_b16 v[58:59], v209 offset:18464
	ds_read_b64_tr_b16 v[62:63], v209 offset:18496
	ds_read_b64_tr_b16 v[66:67], v209 offset:18528
	ds_read_b64_tr_b16 v[56:57], v209 offset:20736
	ds_read_b64_tr_b16 v[60:61], v209 offset:20768
	ds_read_b64_tr_b16 v[64:65], v209 offset:20800
	ds_read_b64_tr_b16 v[68:69], v209 offset:20832
	v_cvt_pk_bf16_f32 v70, v183, v182
	v_cvt_pk_bf16_f32 v71, v179, v178
	v_cvt_pk_bf16_f32 v72, v173, v172
	v_cvt_pk_bf16_f32 v73, v185, v184
	s_waitcnt lgkmcnt(3)
	s_nop 0
	v_mfma_f32_16x16x32_bf16 v[32:35], v[54:57], v[70:73], v[32:35]
	s_waitcnt lgkmcnt(2)
	v_mfma_f32_16x16x32_bf16 v[36:39], v[58:61], v[70:73], v[36:39]
	s_waitcnt lgkmcnt(1)
	v_mfma_f32_16x16x32_bf16 v[40:43], v[62:65], v[70:73], v[40:43]
	s_waitcnt lgkmcnt(0)
	v_mfma_f32_16x16x32_bf16 v[44:47], v[66:69], v[70:73], v[44:47]
	ds_read_b64_tr_b16 v[54:55], v209 offset:23040
	ds_read_b64_tr_b16 v[58:59], v209 offset:23072
	ds_read_b64_tr_b16 v[62:63], v209 offset:23104
	ds_read_b64_tr_b16 v[66:67], v209 offset:23136
	ds_read_b64_tr_b16 v[56:57], v209 offset:25344
	ds_read_b64_tr_b16 v[60:61], v209 offset:25376
	ds_read_b64_tr_b16 v[64:65], v209 offset:25408
	ds_read_b64_tr_b16 v[68:69], v209 offset:25440
	v_cvt_pk_bf16_f32 v70, v177, v176
	v_cvt_pk_bf16_f32 v71, v175, v174
	v_cvt_pk_bf16_f32 v72, v171, v170
	v_cvt_pk_bf16_f32 v73, v181, v180
	s_waitcnt lgkmcnt(3)
	s_nop 0
	v_mfma_f32_16x16x32_bf16 v[32:35], v[54:57], v[70:73], v[32:35]
	s_waitcnt lgkmcnt(2)
	v_mfma_f32_16x16x32_bf16 v[36:39], v[58:61], v[70:73], v[36:39]
	s_waitcnt lgkmcnt(1)
	v_mfma_f32_16x16x32_bf16 v[40:43], v[62:65], v[70:73], v[40:43]
	s_waitcnt lgkmcnt(0)
	v_mfma_f32_16x16x32_bf16 v[44:47], v[66:69], v[70:73], v[44:47]
	ds_read_b64_tr_b16 v[54:55], v209 offset:27648
	ds_read_b64_tr_b16 v[58:59], v209 offset:27680
	ds_read_b64_tr_b16 v[62:63], v209 offset:27712
	ds_read_b64_tr_b16 v[66:67], v209 offset:27744
	ds_read_b64_tr_b16 v[56:57], v209 offset:29952
	ds_read_b64_tr_b16 v[60:61], v209 offset:29984
	ds_read_b64_tr_b16 v[64:65], v209 offset:30016
	ds_read_b64_tr_b16 v[68:69], v209 offset:30048
	v_cvt_pk_bf16_f32 v70, v223, v224
	v_cvt_pk_bf16_f32 v71, v225, v226
	v_cvt_pk_bf16_f32 v72, v227, v50
	v_cvt_pk_bf16_f32 v73, v238, v239
	s_waitcnt lgkmcnt(3)
	s_nop 0
	v_mfma_f32_16x16x32_bf16 v[32:35], v[54:57], v[70:73], v[32:35]
	s_waitcnt lgkmcnt(2)
	v_mfma_f32_16x16x32_bf16 v[36:39], v[58:61], v[70:73], v[36:39]
	s_waitcnt lgkmcnt(1)
	v_mfma_f32_16x16x32_bf16 v[54:57], v[62:65], v[70:73], v[40:43]
	s_waitcnt lgkmcnt(0)
	v_mfma_f32_16x16x32_bf16 v[58:61], v[66:69], v[70:73], v[44:47]
	s_nop 0
	ds_read_b64_tr_b16 v[40:41], v209 offset:32256
	ds_read_b64_tr_b16 v[62:63], v209 offset:32288
	ds_read_b64_tr_b16 v[66:67], v209 offset:32320
	ds_read_b64_tr_b16 v[70:71], v209 offset:32352
	ds_read_b64_tr_b16 v[42:43], v209 offset:34560
	ds_read_b64_tr_b16 v[64:65], v209 offset:34592
	ds_read_b64_tr_b16 v[68:69], v209 offset:34624
	ds_read_b64_tr_b16 v[72:73], v209 offset:34656
	v_cvt_pk_bf16_f32 v74, v240, v241
	v_cvt_pk_bf16_f32 v75, v242, v243
	v_cvt_pk_bf16_f32 v76, v244, v48
	v_cvt_pk_bf16_f32 v77, v245, v246
	s_waitcnt lgkmcnt(3)
	s_nop 0
	v_mfma_f32_16x16x32_bf16 v[44:47], v[40:43], v[74:77], v[32:35]
	s_waitcnt lgkmcnt(2)
	v_mfma_f32_16x16x32_bf16 v[40:43], v[62:65], v[74:77], v[36:39]
	s_waitcnt lgkmcnt(1)
	v_mfma_f32_16x16x32_bf16 v[36:39], v[66:69], v[74:77], v[54:57]
	s_waitcnt lgkmcnt(0)
	v_mfma_f32_16x16x32_bf16 v[32:35], v[70:73], v[74:77], v[58:61]
	s_and_saveexec_b64 s[42:43], s[40:41]
	s_cbranch_execz .LBB0_504
; #define LAS __attribute__((address_space(3)))
; template <bool OWN>
; __device__ __forceinline__ void moba_item(const bf16x8 q0, const bf16x8 q1, LAS unsigned char* lds, int lane, int qb, int n, int qid, bool valid, int smax) {
;     ...
;         } else {
;             const float mo = mst[qid], lo_ = lst[qid];
;             f32x4 old[4];
; #pragma unroll
;             for (int c = 0; c < 4; ++c) old[c] = *(LAS f32x4*)(orow + 4 * ((4 * c + g) ^ (qid & 15)));
;             const float mn = fmaxf(mo, mx), ao = __builtin_amdgcn_exp2f(mo - mn), ap = __builtin_amdgcn_exp2f(mx - mn);
; #pragma unroll
;             for (int c = 0; c < 4; ++c) *(LAS f32x4*)(orow + 4 * ((4 * c + g) ^ (qid & 15))) = old[c] * ao + O[c] * ap;
;             if (g == 0) { mst[qid] = mn; lst[qid] = lo_ * ao + sum * ap; }
;         }
	v_lshl_add_u32 v50, v221, 8, 0
	v_mul_lo_u32 v48, v221, s18
	v_add_u32_e32 v54, v50, v48
	ds_read2st64_b32 v[48:49], v54 offset0:4 offset1:8
	v_bitop3_b32 v55, v221, v186, 15 bitop3:0x6c
	v_lshl_add_u32 v72, v55, 4, v50
	v_bitop3_b32 v55, v221, v210, 15 bitop3:0x6c
	v_lshl_add_u32 v73, v55, 4, v50
	v_bitop3_b32 v55, v221, v211, 15 bitop3:0x6c
	v_lshl_add_u32 v74, v55, 4, v50
	v_bitop3_b32 v55, v221, v212, 15 bitop3:0x6c
	v_lshl_add_u32 v75, v55, 4, v50
	s_waitcnt lgkmcnt(0)
	v_max_f32_e32 v50, v48, v48
	v_max_f32_e32 v55, v51, v51
	v_max_f32_e32 v55, v50, v55
	v_sub_f32_e32 v50, v51, v55
	ds_read_b128 v[56:59], v72 offset:24576
	ds_read_b128 v[60:63], v73 offset:24576
	v_sub_f32_e32 v48, v48, v55
	v_exp_f32_e32 v50, v50
	ds_read_b128 v[64:67], v74 offset:24576
	ds_read_b128 v[68:71], v75 offset:24576
	v_exp_f32_e32 v48, v48
	v_pk_mul_f32 v[44:45], v[44:45], v[50:51] op_sel_hi:[1,0]
	v_pk_mul_f32 v[46:47], v[46:47], v[50:51] op_sel_hi:[1,0]
	v_pk_mul_f32 v[40:41], v[40:41], v[50:51] op_sel_hi:[1,0]
	v_pk_mul_f32 v[42:43], v[42:43], v[50:51] op_sel_hi:[1,0]
	v_pk_mul_f32 v[36:37], v[36:37], v[50:51] op_sel_hi:[1,0]
	v_pk_mul_f32 v[38:39], v[38:39], v[50:51] op_sel_hi:[1,0]
	v_pk_mul_f32 v[32:33], v[32:33], v[50:51] op_sel_hi:[1,0]
	v_pk_mul_f32 v[34:35], v[34:35], v[50:51] op_sel_hi:[1,0]
	s_waitcnt lgkmcnt(3)
	v_pk_fma_f32 v[46:47], v[58:59], v[48:49], v[46:47] op_sel_hi:[1,0,1]
	v_pk_fma_f32 v[44:45], v[56:57], v[48:49], v[44:45] op_sel_hi:[1,0,1]
	s_waitcnt lgkmcnt(2)
	v_pk_fma_f32 v[42:43], v[62:63], v[48:49], v[42:43] op_sel_hi:[1,0,1]
	v_pk_fma_f32 v[40:41], v[60:61], v[48:49], v[40:41] op_sel_hi:[1,0,1]
	s_waitcnt lgkmcnt(1)
	v_pk_fma_f32 v[38:39], v[66:67], v[48:49], v[38:39] op_sel_hi:[1,0,1]
	v_pk_fma_f32 v[36:37], v[64:65], v[48:49], v[36:37] op_sel_hi:[1,0,1]
	s_waitcnt lgkmcnt(0)
	v_pk_fma_f32 v[34:35], v[48:49], v[70:71], v[34:35] op_sel_hi:[0,1,1]
	v_pk_fma_f32 v[32:33], v[48:49], v[68:69], v[32:33] op_sel_hi:[0,1,1]
	ds_write_b128 v72, v[44:47] offset:24576
	ds_write_b128 v73, v[40:43] offset:24576
	ds_write_b128 v74, v[36:39] offset:24576
	ds_write_b128 v75, v[32:35] offset:24576
	s_and_b64 exec, exec, s[38:39]
	v_add_f32_e32 v32, v52, v53
	v_mul_f32_e32 v32, v32, v50
	v_fmac_f32_e32 v32, v49, v48
	ds_write2st64_b32 v54, v55, v32 offset0:4 offset1:8

; template <bool OWN>
; __device__ __forceinline__ void moba_item(const bf16x8 q0, const bf16x8 q1, LAS unsigned char* lds, int lane, int qb, int n, int qid, bool valid, int smax) {
;     ...
;     mx = fmaxf(mx, __shfl_xor(mx, 16)); mx = fmaxf(mx, __shfl_xor(mx, 32));
;     float sum = 0.f;
; #pragma unroll
;     for (int sp = 0; sp < 4; ++sp) if (!OWN || 2 * sp <= smax) {
; #pragma unroll
;         for (int t = 0; t < 4; ++t)
; #pragma unroll
;             for (int jj = 0; jj < 4; ++jj) { const float pv = __builtin_amdgcn_exp2f(S[4 * sp + t][jj] - mx); S[4 * sp + t][jj] = pv; sum += pv; }
.LBB0_522:
	v_mov_b32_e32 v99, v97
	s_nop 1
	v_permlane16_swap_b32_e32 v97, v99
	v_max_f32_e32 v97, v97, v97
	s_waitcnt lgkmcnt(0)
	v_max_f32_e32 v99, v99, v99
	v_max_f32_e32 v99, v97, v99
	v_mov_b32_e32 v98, v99
	s_nop 1
	v_permlane32_swap_b32_e32 v99, v98
	s_and_b64 vcc, exec, s[40:41]
	s_waitcnt lgkmcnt(0)
	v_max_f32_e32 v98, v98, v98
	v_max_f32_e32 v170, v99, v98
	v_mov_b32_e32 v98, 0
	s_cbranch_vccnz .LBB0_526
	v_sub_f32_e32 v92, v92, v170
	v_exp_f32_e32 v92, v92
	v_sub_f32_e32 v93, v93, v170
	v_exp_f32_e32 v93, v93
	v_sub_f32_e32 v94, v94, v170
	v_exp_f32_e32 v94, v94
	v_sub_f32_e32 v95, v95, v170
	v_exp_f32_e32 v95, v95
	v_sub_f32_e32 v88, v88, v170
	v_add_f32_e32 v98, 0, v92
	v_exp_f32_e32 v88, v88
	v_sub_f32_e32 v89, v89, v170
	v_add_f32_e32 v98, v93, v98
	v_exp_f32_e32 v89, v89
	v_sub_f32_e32 v90, v90, v170
	v_add_f32_e32 v98, v94, v98
	v_exp_f32_e32 v90, v90
	v_sub_f32_e32 v91, v91, v170
	v_add_f32_e32 v98, v95, v98
	v_exp_f32_e32 v91, v91
	v_sub_f32_e32 v68, v68, v170
	v_add_f32_e32 v98, v88, v98
	v_exp_f32_e32 v68, v68
	v_sub_f32_e32 v69, v69, v170
	v_add_f32_e32 v98, v89, v98
	v_exp_f32_e32 v69, v69
	v_sub_f32_e32 v70, v70, v170
	v_add_f32_e32 v98, v90, v98
	v_exp_f32_e32 v70, v70
	v_sub_f32_e32 v71, v71, v170
	v_add_f32_e32 v98, v91, v98
	v_exp_f32_e32 v71, v71
	v_sub_f32_e32 v64, v64, v170
	v_add_f32_e32 v98, v68, v98
	v_exp_f32_e32 v64, v64
	v_sub_f32_e32 v65, v65, v170
	v_add_f32_e32 v98, v69, v98
	v_exp_f32_e32 v65, v65
	v_sub_f32_e32 v66, v66, v170
	v_add_f32_e32 v98, v70, v98
	v_exp_f32_e32 v66, v66
	v_sub_f32_e32 v67, v67, v170
	v_add_f32_e32 v98, v71, v98
	v_exp_f32_e32 v67, v67
	v_add_f32_e32 v98, v64, v98
	v_add_f32_e32 v98, v65, v98
	v_add_f32_e32 v98, v66, v98
	v_add_f32_e32 v98, v67, v98
	s_and_b64 vcc, exec, s[42:43]
	s_cbranch_vccz .LBB0_527

; #define LAS __attribute__((address_space(3)))
; __device__ __forceinline__ unsigned pk2(float lo, float hi) { f32x2_t v = {lo, hi}; bf16x2_t b = __builtin_convertvector(v, bf16x2_t); return __builtin_bit_cast(unsigned, b); }
; __device__ __forceinline__ f32x4 mfma16(bf16x8 a, bf16x8 b, f32x4 c) { return __builtin_amdgcn_mfma_f32_16x16x32_bf16(a, b, c, 0, 0, 0); }
; __device__ __forceinline__ s16x4 vtr(const LAS unsigned char* p) { return __builtin_bit_cast(s16x4, __builtin_amdgcn_ds_read_tr16_b64_v4i16((LAS s16x4*)p)); }
; #define SBAR() __builtin_amdgcn_sched_barrier(0)
; #define SBAR() __builtin_amdgcn_sched_barrier(0)
; template <bool OWN>
; __device__ __forceinline__ void moba_item(const bf16x8 q0, const bf16x8 q1, LAS unsigned char* lds, int lane, int qb, int n, int qid, bool valid, int smax) {
;     ...
;     sum += __shfl_xor(sum, 16); sum += __shfl_xor(sum, 32);
;     f32x4 O[4];
; #pragma unroll
;     for (int c = 0; c < 4; ++c) O[c] = (f32x4){0.f, 0.f, 0.f, 0.f};
; #pragma unroll
;     for (int s8 = 0; s8 < 8; ++s8) if (!OWN || (s8 >> 1) * 2 <= smax) {
;         s16x4 vl[4][2];
; #pragma unroll
;         for (int c = 0; c < 4; ++c) { const LAS unsigned char* vp = vbase + (32 * s8) * 144 + 32 * c; vl[c][0] = vtr(vp); vl[c][1] = vtr(vp + 16 * 144); }
;         const int t0 = 2 * s8; v4u pw; pw.x = pk2(S[t0][0], S[t0][1]); pw.y = pk2(S[t0][2], S[t0][3]); pw.z = pk2(S[t0 + 1][0], S[t0 + 1][1]); pw.w = pk2(S[t0 + 1][2], S[t0 + 1][3]);
;         const bf16x8 pb = __builtin_bit_cast(bf16x8, pw);
;         SBAR();
; #pragma unroll
;         for (int c = 0; c < 4; ++c) { const s16x4 lo = vl[c][0], hi = vl[c][1];
;             const bf16x8 vf = (bf16x8){lo[0], lo[1], lo[2], lo[3], hi[0], hi[1], hi[2], hi[3]};
;             O[c] = mfma16(vf, pb, O[c]); }
;         SBAR();
.LBB0_530:
	v_mov_b32_e32 v96, v98
	s_nop 1
	v_permlane16_swap_b32_e32 v98, v96
	s_and_b64 vcc, exec, s[40:41]
	s_waitcnt lgkmcnt(0)
	v_add_f32_e32 v171, v98, v96
	v_mov_b32_e32 v172, v171
	s_nop 1
	v_permlane32_swap_b32_e32 v171, v172
	s_cbranch_vccnz .LBB0_532
	ds_read_b64_tr_b16 v[96:97], v209
	s_waitcnt vmcnt(0)
	ds_read_b64_tr_b16 v[100:101], v209 offset:32
	ds_read_b64_tr_b16 v[174:175], v209 offset:64
	ds_read_b64_tr_b16 v[178:179], v209 offset:96
	ds_read_b64_tr_b16 v[98:99], v209 offset:2304
	ds_read_b64_tr_b16 v[102:103], v209 offset:2336
	ds_read_b64_tr_b16 v[176:177], v209 offset:2368
	ds_read_b64_tr_b16 v[180:181], v209 offset:2400
	v_cvt_pk_bf16_f32 v182, v92, v93
	v_cvt_pk_bf16_f32 v183, v94, v95
	v_cvt_pk_bf16_f32 v184, v88, v89
	v_cvt_pk_bf16_f32 v185, v90, v91
	s_waitcnt lgkmcnt(3)
	s_nop 0
	v_mfma_f32_16x16x32_bf16 v[92:95], v[96:99], v[182:185], 0
	s_waitcnt lgkmcnt(2)
	v_mfma_f32_16x16x32_bf16 v[96:99], v[100:103], v[182:185], 0
	s_waitcnt lgkmcnt(1)
	v_mfma_f32_16x16x32_bf16 v[100:103], v[174:177], v[182:185], 0
	s_waitcnt lgkmcnt(0)
	v_mfma_f32_16x16x32_bf16 v[88:91], v[178:181], v[182:185], 0
	s_and_b64 vcc, exec, s[40:41]
	s_cbranch_vccz .LBB0_533
	s_branch .LBB0_534

; #define LAS __attribute__((address_space(3)))
; __device__ __forceinline__ unsigned pk2(float lo, float hi) { f32x2_t v = {lo, hi}; bf16x2_t b = __builtin_convertvector(v, bf16x2_t); return __builtin_bit_cast(unsigned, b); }
; __device__ __forceinline__ f32x4 mfma16(bf16x8 a, bf16x8 b, f32x4 c) { return __builtin_amdgcn_mfma_f32_16x16x32_bf16(a, b, c, 0, 0, 0); }
; __device__ __forceinline__ s16x4 vtr(const LAS unsigned char* p) { return __builtin_bit_cast(s16x4, __builtin_amdgcn_ds_read_tr16_b64_v4i16((LAS s16x4*)p)); }
; #define SBAR() __builtin_amdgcn_sched_barrier(0)
; __device__ __forceinline__ void attnA_unit(const Ctx& C, int unit) {
;     ...
;         for (int kt = 0; kt < 10; ++kt)
; #pragma unroll
;             for (int jj = 0; jj < 4; ++jj) mx = fmaxf(mx, S[kt][jj]);
;         mx = fmaxf(mx, __shfl_xor(mx, 16)); mx = fmaxf(mx, __shfl_xor(mx, 32));
;         float sum = 0.f; const float mxl = mx * 1.4426950408889634f;
; #pragma unroll
;         for (int kt = 0; kt < 10; ++kt)
; #pragma unroll
;             for (int jj = 0; jj < 4; ++jj) { const float pv = __builtin_amdgcn_exp2f(S[kt][jj] * 1.4426950408889634f - mxl); S[kt][jj] = pv; sum += pv; }
;         sum += __shfl_xor(sum, 16); sum += __shfl_xor(sum, 32);
;         f32x4 O[4];
; #pragma unroll
;         for (int c = 0; c < 4; ++c) O[c] = (f32x4){0.f, 0.f, 0.f, 0.f};
;         const LAS unsigned char* vrd = Vst + (8 * g + (i16 >> 2)) * 144 + 8 * (i16 & 3);
;         LAS unsigned char* vwr = Vst + (lane >> 3) * 144 + (lane & 7) * 16;
; #pragma unroll
;         for (int s5 = 0; s5 < 5; ++s5) {
; #pragma unroll
;             for (int i = 0; i < 4; ++i) *(LAS v4u*)(vwr + 8 * i * 144) = vreg[s5][i];
;             v4u pw; pw.x = pk2(S[2 * s5][0], S[2 * s5][1]); pw.y = pk2(S[2 * s5][2], S[2 * s5][3]); pw.z = pk2(S[2 * s5 + 1][0], S[2 * s5 + 1][1]); pw.w = pk2(S[2 * s5 + 1][2], S[2 * s5 + 1][3]);
;             const bf16x8 pb = __builtin_bit_cast(bf16x8, pw);
;             s16x4 vl[4][2];
; #pragma unroll
;             for (int c = 0; c < 4; ++c) { vl[c][0] = vtr(vrd + 32 * c); vl[c][1] = vtr(vrd + 32 * c + 4 * 144); }
;             SBAR();
; #pragma unroll
;             for (int c = 0; c < 4; ++c) { const s16x4 lo = vl[c][0], hi = vl[c][1];
;                 const bf16x8 vf = (bf16x8){lo[0], lo[1], lo[2], lo[3], hi[0], hi[1], hi[2], hi[3]};
;                 O[c] = mfma16(vf, pb, O[c]); }
.LBB0_567:
	v_max3_f32 v81, v146, s17, v152
	v_max3_f32 v81, v81, v147, v149
	v_max3_f32 v81, v81, v151, v148
	v_max3_f32 v81, v81, v150, v128
	v_max3_f32 v81, v81, v126, v127
	v_max3_f32 v81, v81, v124, v125
	v_max3_f32 v81, v81, v122, v123
	v_max3_f32 v81, v81, v120, v121
	v_max3_f32 v81, v81, v118, v119
	v_max3_f32 v81, v81, v116, v117
	v_max3_f32 v81, v81, v114, v115
	v_max3_f32 v81, v81, v112, v113
	v_max3_f32 v81, v81, v110, v111
	v_max3_f32 v81, v81, v108, v109
	v_max3_f32 v81, v81, v102, v103
	v_max3_f32 v81, v81, v100, v101
	v_max3_f32 v81, v81, v97, v96
	v_max3_f32 v81, v81, v85, v84
	v_max3_f32 v81, v81, v83, v82
	v_max3_f32 v81, v81, v86, v80
	v_mov_b32_e32 v87, v81
	s_nop 1
	v_permlane16_swap_b32_e32 v81, v87
	s_waitcnt vmcnt(19)
	ds_write_b128 v143, v[64:67] offset:2240
	s_waitcnt vmcnt(18)
	ds_write_b128 v143, v[68:71] offset:3392
	s_waitcnt vmcnt(17)
	ds_write_b128 v143, v[72:75] offset:4544
	s_waitcnt vmcnt(16)
	ds_write_b128 v143, v[76:79] offset:5696
	ds_read_b64_tr_b16 v[64:65], v144 offset:2240
	ds_read_b64_tr_b16 v[68:69], v144 offset:2272
	ds_read_b64_tr_b16 v[72:73], v144 offset:2304
	ds_read_b64_tr_b16 v[76:77], v144 offset:2336
	ds_read_b64_tr_b16 v[66:67], v144 offset:2816
	ds_read_b64_tr_b16 v[70:71], v144 offset:2848
	ds_read_b64_tr_b16 v[74:75], v144 offset:2880
	ds_read_b64_tr_b16 v[78:79], v144 offset:2912
	s_waitcnt lgkmcnt(12)
	v_max_f32_e32 v87, v87, v87
	v_max_f32_e32 v81, v81, v87
	v_mov_b32_e32 v87, v81
	s_nop 1
	v_permlane32_swap_b32_e32 v81, v87
	s_waitcnt lgkmcnt(0)
	v_max_f32_e32 v87, v87, v87
	v_max_f32_e32 v81, v81, v87
	v_pk_mul_f32 v[88:89], v[80:81], s[82:83] op_sel_hi:[1,0]
	s_nop 0
	v_fma_f32 v80, v146, s82, -v89
	v_fma_f32 v87, v152, s82, -v89
	v_exp_f32_e32 v80, v80
	v_fma_f32 v90, v147, s82, -v89
	v_exp_f32_e32 v87, v87
	v_fma_f32 v91, v149, s82, -v89
	v_exp_f32_e32 v90, v90
	v_fma_f32 v92, v151, s82, -v89
	v_exp_f32_e32 v91, v91
	v_fma_f32 v93, v148, s82, -v89
	v_exp_f32_e32 v92, v92
	v_add_f32_e32 v95, 0, v80
	v_fma_f32 v94, v150, s82, -v89
	v_exp_f32_e32 v93, v93
	v_add_f32_e32 v95, v87, v95
	v_add_f32_e32 v95, v90, v95
	v_exp_f32_e32 v94, v94
	v_fma_f32 v98, v128, s82, -v89
	v_add_f32_e32 v95, v91, v95
	v_exp_f32_e32 v98, v98
	v_fma_f32 v99, v126, s82, -v89
	v_add_f32_e32 v95, v92, v95
	v_exp_f32_e32 v99, v99
	v_fma_f32 v104, v127, s82, -v89
	v_add_f32_e32 v95, v93, v95
	v_exp_f32_e32 v104, v104
	v_fma_f32 v105, v124, s82, -v89
	v_add_f32_e32 v95, v94, v95
	v_exp_f32_e32 v105, v105
	v_fma_f32 v106, v125, s82, -v89
	v_add_f32_e32 v95, v98, v95
	v_exp_f32_e32 v106, v106
	v_fma_f32 v107, v122, s82, -v89
	v_add_f32_e32 v95, v99, v95
	v_exp_f32_e32 v107, v107
	v_fma_f32 v122, v123, s82, -v89
	v_add_f32_e32 v95, v104, v95
	v_exp_f32_e32 v122, v122
	v_fma_f32 v120, v120, s82, -v89
	v_add_f32_e32 v95, v105, v95
	v_exp_f32_e32 v120, v120
	v_fma_f32 v121, v121, s82, -v89
	v_add_f32_e32 v95, v106, v95
	v_exp_f32_e32 v121, v121
	v_fma_f32 v118, v118, s82, -v89
	v_add_f32_e32 v95, v107, v95
	v_exp_f32_e32 v118, v118
	v_fma_f32 v119, v119, s82, -v89
	v_add_f32_e32 v95, v122, v95
	v_exp_f32_e32 v119, v119
	v_fma_f32 v116, v116, s82, -v89
	v_add_f32_e32 v95, v120, v95
	v_exp_f32_e32 v116, v116
	v_fma_f32 v117, v117, s82, -v89
	v_add_f32_e32 v95, v121, v95
	v_exp_f32_e32 v117, v117
	v_fma_f32 v114, v114, s82, -v89
	v_add_f32_e32 v95, v118, v95
	v_exp_f32_e32 v114, v114
	v_fma_f32 v115, v115, s82, -v89
	v_add_f32_e32 v95, v119, v95
	v_exp_f32_e32 v115, v115
	v_fma_f32 v112, v112, s82, -v89
	v_add_f32_e32 v95, v116, v95
	v_exp_f32_e32 v112, v112
	v_fma_f32 v113, v113, s82, -v89
	v_add_f32_e32 v95, v117, v95
	v_exp_f32_e32 v113, v113
	v_fma_f32 v110, v110, s82, -v89
	v_add_f32_e32 v95, v114, v95
	v_exp_f32_e32 v110, v110
	v_fma_f32 v111, v111, s82, -v89
	v_add_f32_e32 v95, v115, v95
	v_exp_f32_e32 v111, v111
	v_fma_f32 v108, v108, s82, -v89
	v_add_f32_e32 v95, v112, v95
	v_exp_f32_e32 v108, v108
	v_fma_f32 v109, v109, s82, -v89
	v_add_f32_e32 v95, v113, v95
	v_exp_f32_e32 v109, v109
	v_fma_f32 v102, v102, s82, -v89
	v_add_f32_e32 v95, v110, v95
	v_exp_f32_e32 v102, v102
	v_fma_f32 v103, v103, s82, -v89
	v_add_f32_e32 v95, v111, v95
	v_exp_f32_e32 v103, v103
	v_fma_f32 v100, v100, s82, -v89
	v_add_f32_e32 v95, v108, v95
	v_exp_f32_e32 v100, v100
	v_fma_f32 v101, v101, s82, -v89
	v_add_f32_e32 v95, v109, v95
	v_exp_f32_e32 v101, v101
	v_fma_f32 v97, v97, s82, -v89
	v_add_f32_e32 v95, v102, v95
	v_exp_f32_e32 v97, v97
	v_fma_f32 v96, v96, s82, -v89
	v_add_f32_e32 v95, v103, v95
	v_exp_f32_e32 v96, v96
	v_fma_f32 v85, v85, s82, -v89
	v_add_f32_e32 v95, v100, v95
	v_exp_f32_e32 v123, v85
	v_fma_f32 v84, v84, s82, -v89
	v_add_f32_e32 v95, v101, v95
	v_exp_f32_e32 v124, v84
	v_fma_f32 v83, v83, s82, -v89
	v_add_f32_e32 v84, v97, v95
	v_exp_f32_e32 v95, v83
	v_fma_f32 v82, v82, s82, -v89
	v_add_f32_e32 v84, v96, v84
	v_exp_f32_e32 v125, v82
	v_fma_f32 v82, v86, s82, -v89
	v_add_f32_e32 v84, v123, v84
	v_exp_f32_e32 v86, v82
	v_sub_f32_e32 v82, v88, v89
	v_add_f32_e32 v84, v124, v84
	v_exp_f32_e32 v88, v82
	v_add_f32_e32 v82, v95, v84
	v_add_f32_e32 v82, v125, v82
	v_add_f32_e32 v82, v86, v82
	v_add_f32_e32 v82, v88, v82
	v_mov_b32_e32 v83, v82
	s_nop 1
	v_permlane16_swap_b32_e32 v82, v83
	v_cvt_pk_bf16_f32 v84, v92, v93
	v_cvt_pk_bf16_f32 v85, v94, v98
	s_waitcnt lgkmcnt(0)
	v_add_f32_e32 v89, v82, v83
	v_mov_b32_e32 v126, v89
	s_nop 1
	v_permlane32_swap_b32_e32 v89, v126
	v_cvt_pk_bf16_f32 v82, v80, v87
	v_cvt_pk_bf16_f32 v83, v90, v91
	s_nop 1
	v_mfma_f32_16x16x32_bf16 v[64:67], v[64:67], v[82:85], 0
	v_mfma_f32_16x16x32_bf16 v[68:71], v[68:71], v[82:85], 0
	v_mfma_f32_16x16x32_bf16 v[72:75], v[72:75], v[82:85], 0
	v_mfma_f32_16x16x32_bf16 v[76:79], v[76:79], v[82:85], 0
	s_waitcnt vmcnt(15)
; #define LAS __attribute__((address_space(3)))
; __device__ __forceinline__ unsigned pk2(float lo, float hi) { f32x2_t v = {lo, hi}; bf16x2_t b = __builtin_convertvector(v, bf16x2_t); return __builtin_bit_cast(unsigned, b); }
; __device__ __forceinline__ f32x4 mfma16(bf16x8 a, bf16x8 b, f32x4 c) { return __builtin_amdgcn_mfma_f32_16x16x32_bf16(a, b, c, 0, 0, 0); }
; __device__ __forceinline__ s16x4 vtr(const LAS unsigned char* p) { return __builtin_bit_cast(s16x4, __builtin_amdgcn_ds_read_tr16_b64_v4i16((LAS s16x4*)p)); }
; #define SBAR() __builtin_amdgcn_sched_barrier(0)
; #define SBAR() __builtin_amdgcn_sched_barrier(0)
; __device__ __forceinline__ void attnA_unit(const Ctx& C, int unit) {
;     ...
; #pragma unroll
;         for (int s5 = 0; s5 < 5; ++s5) {
; #pragma unroll
;             for (int i = 0; i < 4; ++i) *(LAS v4u*)(vwr + 8 * i * 144) = vreg[s5][i];
;             v4u pw; pw.x = pk2(S[2 * s5][0], S[2 * s5][1]); pw.y = pk2(S[2 * s5][2], S[2 * s5][3]); pw.z = pk2(S[2 * s5 + 1][0], S[2 * s5 + 1][1]); pw.w = pk2(S[2 * s5 + 1][2], S[2 * s5 + 1][3]);
;             const bf16x8 pb = __builtin_bit_cast(bf16x8, pw);
;             s16x4 vl[4][2];
; #pragma unroll
;             for (int c = 0; c < 4; ++c) { vl[c][0] = vtr(vrd + 32 * c); vl[c][1] = vtr(vrd + 32 * c + 4 * 144); }
;             SBAR();
; #pragma unroll
;             for (int c = 0; c < 4; ++c) { const s16x4 lo = vl[c][0], hi = vl[c][1];
;                 const bf16x8 vf = (bf16x8){lo[0], lo[1], lo[2], lo[3], hi[0], hi[1], hi[2], hi[3]};
;                 O[c] = mfma16(vf, pb, O[c]); }
;             SBAR();
;         }
;         const float inv = __builtin_amdgcn_rcpf(sum);
;         LAS bf16* op = OG + (grp * 256 + (tq - T0)) * 64 + 4 * g;
; #pragma unroll
;         for (int c = 0; c < 4; ++c) { v2u w; w.x = pk2(O[c][0] * inv, O[c][1] * inv); w.y = pk2(O[c][2] * inv, O[c][3] * inv); *(LAS v2u*)(op + 16 * c) = w; }
;         if (g == 0) LSEl[grp * 256 + (tq - T0)] = mx + __logf(sum);
	ds_write_b128 v143, v[48:51] offset:2240
	s_waitcnt vmcnt(14)
	ds_write_b128 v143, v[52:55] offset:3392
	s_waitcnt vmcnt(13)
	ds_write_b128 v143, v[56:59] offset:4544
	s_waitcnt vmcnt(12)
	ds_write_b128 v143, v[60:63] offset:5696
	ds_read_b64_tr_b16 v[54:55], v144 offset:2816
	ds_read_b64_tr_b16 v[52:53], v144 offset:2240
	ds_read_b64_tr_b16 v[56:57], v144 offset:2272
	ds_read_b64_tr_b16 v[58:59], v144 offset:2848
	ds_read_b64_tr_b16 v[60:61], v144 offset:2304
	ds_read_b64_tr_b16 v[62:63], v144 offset:2880
	ds_read_b64_tr_b16 v[82:83], v144 offset:2336
	ds_read_b64_tr_b16 v[84:85], v144 offset:2912
	v_cvt_pk_bf16_f32 v48, v99, v104
	v_cvt_pk_bf16_f32 v49, v105, v106
	v_cvt_pk_bf16_f32 v50, v107, v122
	v_cvt_pk_bf16_f32 v51, v120, v121
	s_waitcnt lgkmcnt(6)
	s_nop 0
	v_mfma_f32_16x16x32_bf16 v[52:55], v[52:55], v[48:51], v[64:67]
	s_waitcnt lgkmcnt(4)
	v_mfma_f32_16x16x32_bf16 v[56:59], v[56:59], v[48:51], v[68:71]
	s_waitcnt lgkmcnt(2)
	v_mfma_f32_16x16x32_bf16 v[60:63], v[60:63], v[48:51], v[72:75]
	s_waitcnt lgkmcnt(0)
	v_mfma_f32_16x16x32_bf16 v[48:51], v[82:85], v[48:51], v[76:79]
	s_waitcnt vmcnt(11)
	ds_write_b128 v143, v[32:35] offset:2240
	s_waitcnt vmcnt(10)
	ds_write_b128 v143, v[36:39] offset:3392
	s_waitcnt vmcnt(9)
	ds_write_b128 v143, v[40:43] offset:4544
	s_waitcnt vmcnt(8)
	ds_write_b128 v143, v[44:47] offset:5696
	ds_read_b64_tr_b16 v[38:39], v144 offset:2816
	ds_read_b64_tr_b16 v[36:37], v144 offset:2240
	ds_read_b64_tr_b16 v[40:41], v144 offset:2272
	ds_read_b64_tr_b16 v[42:43], v144 offset:2848
	ds_read_b64_tr_b16 v[44:45], v144 offset:2304
	ds_read_b64_tr_b16 v[46:47], v144 offset:2880
	ds_read_b64_tr_b16 v[64:65], v144 offset:2336
	ds_read_b64_tr_b16 v[66:67], v144 offset:2912
	v_cvt_pk_bf16_f32 v32, v118, v119
	v_cvt_pk_bf16_f32 v33, v116, v117
	v_cvt_pk_bf16_f32 v34, v114, v115
	v_cvt_pk_bf16_f32 v35, v112, v113
	s_waitcnt lgkmcnt(6)
	s_nop 0
	v_mfma_f32_16x16x32_bf16 v[36:39], v[36:39], v[32:35], v[52:55]
	s_waitcnt lgkmcnt(4)
	v_mfma_f32_16x16x32_bf16 v[40:43], v[40:43], v[32:35], v[56:59]
	s_waitcnt lgkmcnt(2)
	v_mfma_f32_16x16x32_bf16 v[44:47], v[44:47], v[32:35], v[60:63]
	s_waitcnt lgkmcnt(0)
	v_mfma_f32_16x16x32_bf16 v[32:35], v[64:67], v[32:35], v[48:51]
	s_waitcnt vmcnt(7)
	ds_write_b128 v143, v[16:19] offset:2240
	s_waitcnt vmcnt(6)
	ds_write_b128 v143, v[20:23] offset:3392
	s_waitcnt vmcnt(5)
	ds_write_b128 v143, v[24:27] offset:4544
	s_waitcnt vmcnt(4)
	ds_write_b128 v143, v[28:31] offset:5696
	ds_read_b64_tr_b16 v[22:23], v144 offset:2816
	ds_read_b64_tr_b16 v[20:21], v144 offset:2240
	ds_read_b64_tr_b16 v[24:25], v144 offset:2272
	ds_read_b64_tr_b16 v[26:27], v144 offset:2848
	ds_read_b64_tr_b16 v[28:29], v144 offset:2304
	ds_read_b64_tr_b16 v[30:31], v144 offset:2880
	ds_read_b64_tr_b16 v[48:49], v144 offset:2336
	ds_read_b64_tr_b16 v[50:51], v144 offset:2912
	v_cvt_pk_bf16_f32 v16, v110, v111
	v_cvt_pk_bf16_f32 v17, v108, v109
	v_cvt_pk_bf16_f32 v18, v102, v103
	v_cvt_pk_bf16_f32 v19, v100, v101
	s_waitcnt lgkmcnt(6)
	s_nop 0
	v_mfma_f32_16x16x32_bf16 v[20:23], v[20:23], v[16:19], v[36:39]
	s_waitcnt lgkmcnt(4)
	v_mfma_f32_16x16x32_bf16 v[24:27], v[24:27], v[16:19], v[40:43]
	s_waitcnt lgkmcnt(2)
	v_mfma_f32_16x16x32_bf16 v[28:31], v[28:31], v[16:19], v[44:47]
	s_waitcnt lgkmcnt(0)
	v_mfma_f32_16x16x32_bf16 v[16:19], v[48:51], v[16:19], v[32:35]
	s_waitcnt vmcnt(3)
	ds_write_b128 v143, v[0:3] offset:2240
	s_waitcnt vmcnt(2)
	ds_write_b128 v143, v[4:7] offset:3392
	s_waitcnt vmcnt(1)
	ds_write_b128 v143, v[8:11] offset:4544
	s_waitcnt vmcnt(0)
	ds_write_b128 v143, v[12:15] offset:5696
	ds_read_b64_tr_b16 v[6:7], v144 offset:2816
	ds_read_b64_tr_b16 v[4:5], v144 offset:2240
	ds_read_b64_tr_b16 v[8:9], v144 offset:2272
	ds_read_b64_tr_b16 v[10:11], v144 offset:2848
	ds_read_b64_tr_b16 v[12:13], v144 offset:2304
	ds_read_b64_tr_b16 v[14:15], v144 offset:2880
	ds_read_b64_tr_b16 v[32:33], v144 offset:2336
	ds_read_b64_tr_b16 v[34:35], v144 offset:2912
	v_cvt_pk_bf16_f32 v0, v97, v96
	v_cvt_pk_bf16_f32 v1, v123, v124
	v_cvt_pk_bf16_f32 v2, v95, v125
	v_cvt_pk_bf16_f32 v3, v86, v88
	s_waitcnt lgkmcnt(6)
	s_nop 0
	v_mfma_f32_16x16x32_bf16 v[4:7], v[4:7], v[0:3], v[20:23]
	s_waitcnt lgkmcnt(4)
	v_mfma_f32_16x16x32_bf16 v[8:11], v[8:11], v[0:3], v[24:27]
	s_waitcnt lgkmcnt(2)
	v_mfma_f32_16x16x32_bf16 v[12:15], v[12:15], v[0:3], v[28:31]
	s_waitcnt lgkmcnt(0)
	v_mfma_f32_16x16x32_bf16 v[16:19], v[32:35], v[0:3], v[16:19]
	v_add_f32_e32 v1, v89, v126
	v_rcp_f32_e32 v2, v1
	v_subrev_u32_e32 v0, s19, v145
	v_add_u32_e32 v0, s68, v0
	v_lshl_add_u32 v3, v0, 7, v136
	v_pk_mul_f32 v[4:5], v[2:3], v[4:5] op_sel_hi:[0,1]
	v_pk_mul_f32 v[6:7], v[2:3], v[6:7] op_sel_hi:[0,1]
	v_cvt_pk_bf16_f32 v4, v4, v5
	v_cvt_pk_bf16_f32 v5, v6, v7
	v_pk_mul_f32 v[6:7], v[2:3], v[8:9] op_sel_hi:[0,1]
	v_pk_mul_f32 v[8:9], v[2:3], v[10:11] op_sel_hi:[0,1]
	v_cvt_pk_bf16_f32 v6, v6, v7
	v_cvt_pk_bf16_f32 v7, v8, v9
	v_add_u32_e32 v8, 0xa000, v3
	ds_write2_b64 v8, v[4:5], v[6:7] offset0:8 offset1:12
	v_pk_mul_f32 v[4:5], v[2:3], v[12:13] op_sel_hi:[0,1]
	v_pk_mul_f32 v[6:7], v[2:3], v[14:15] op_sel_hi:[0,1]
	v_cvt_pk_bf16_f32 v4, v4, v5
	v_cvt_pk_bf16_f32 v5, v6, v7
	v_pk_mul_f32 v[6:7], v[2:3], v[16:17] op_sel_hi:[0,1]
	v_pk_mul_f32 v[2:3], v[2:3], v[18:19] op_sel_hi:[0,1]
	v_cvt_pk_bf16_f32 v6, v6, v7
	v_cvt_pk_bf16_f32 v7, v2, v3
	ds_write2_b64 v8, v[4:5], v[6:7] offset0:16 offset1:20
	s_and_saveexec_b64 s[68:69], vcc
	s_cbranch_execz .LBB0_559
	v_cmp_gt_f32_e64 s[56:57], s0, v1
	v_lshl_add_u32 v0, v0, 2, 0
	v_add_u32_e32 v0, 0x22040, v0
	v_cndmask_b32_e64 v2, 0, 32, s[56:57]
	v_ldexp_f32 v1, v1, v2
	v_log_f32_e32 v1, v1
	v_cndmask_b32_e64 v2, 0, v235, s[56:57]
	v_mul_f32_e32 v3, 0x3f317217, v1
	v_fma_f32 v3, v1, s1, -v3
	v_fmac_f32_e32 v3, 0x3377d1cf, v1
	v_fmac_f32_e32 v3, 0x3f317217, v1
	v_cmp_lt_f32_e64 s[56:57], |v1|, s75
	s_nop 1
	v_cndmask_b32_e64 v1, v1, v3, s[56:57]
	v_sub_f32_e32 v1, v1, v2
	v_add_f32_e32 v1, v81, v1
	ds_write_b32 v0, v1
	s_branch .LBB0_559
